# GEMM K-loops without any s_setprio (both wave halves at equal priority), on top of nt7
# speedup vs baseline: 1.0102x; 1.0102x over previous
; #define PG8_STAGE(bufoff, gbase, voff) do { _Pragma("unroll") for (int _i = 0; _i < 2; ++_i) \
;         __builtin_amdgcn_global_load_lds((const unsigned*)((const char*)(gbase) + (voff)[_i]), (PG8_LAS unsigned*)(lds + (bufoff) + ldsw + _i * 8192), 16, 0, 0); } while (0)
; #define PG8_LDA(dst, b, h) do { _Pragma("unroll") for (int m = 0; m < 4; ++m) _Pragma("unroll") for (int k = 0; k < 2; ++k) dst[m][k] = *(const PG8_LAS bf16x8*)(lds + PG8_SA(b, h) + aoff + m * 2048 + k * 1024); } while (0)
; #define PG8_LDB(dst, b, h) do { _Pragma("unroll") for (int n = 0; n < 2; ++n) _Pragma("unroll") for (int k = 0; k < 2; ++k) dst[n][k] = *(const PG8_LAS bf16x8*)(lds + PG8_SB(b, h) + boff + n * 2048 + k * 1024); } while (0)
; #define PG8_MMA(ai, bj, At, Bt) do { __builtin_amdgcn_s_setprio(1); _Pragma("unroll") for (int m = 0; m < 4; ++m) _Pragma("unroll") for (int n = 0; n < 2; ++n) _Pragma("unroll") for (int k = 0; k < 2; ++k) \
;         acc[ai][bj][m][n] = __builtin_amdgcn_mfma_f32_16x16x32_bf16(Bt[n][k], At[m][k], acc[ai][bj][m][n], 0, 0, 0); __builtin_amdgcn_s_setprio(0); } while (0)
; #define PG8_WAIT_V(n) asm volatile("s_waitcnt vmcnt(" #n ")" ::: "memory")
; #define PG8_WAIT_L(n) asm volatile("s_waitcnt lgkmcnt(" #n ")" ::: "memory")
; #define PG8_BAR __builtin_amdgcn_s_barrier()
; #define PG8_SCHED __builtin_amdgcn_sched_barrier(0)
; template <class Epi, class Sched, bool ALIGN_EPI = false, bool SP2 = false>
; __device__ __forceinline__ void gemm_phase(PG8_LAS unsigned char* lds, const Gemm g, const Sched& S, const Epi& E) {
;     ...
;             PG8_LDB(B0, 0, 0); PG8_LDB(B1, 0, 1); PG8_SCHED; PG8_LDA(At, 0, 0); PG8_STAGE(PG8_SA(1, 1), a1 + hstep, voffA);
;             PG8_WAIT_V(8); PG8_WAIT_L(0); PG8_BAR; PG8_MMA(0, 0, At, B0); PG8_MMA(0, 1, At, B1); PG8_BAR; PG8_SCHED;
;             PG8_LDA(At, 0, 1); PG8_STAGE(PG8_SB(0, 0), b2, voffB); PG8_STAGE(PG8_SB(0, 1), b2 + hstep, voffB); PG8_STAGE(PG8_SA(0, 0), a2, voffA);
;             PG8_WAIT_V(8); PG8_WAIT_L(0); PG8_BAR; PG8_MMA(1, 0, At, B0); PG8_MMA(1, 1, At, B1); PG8_BAR; PG8_SCHED;
.LBB0_180:
	ds_read_b128 v[130:133], v242
	ds_read_b128 v[134:137], v242 offset:1024
	ds_read_b128 v[138:141], v242 offset:2048
	ds_read_b128 v[142:145], v242 offset:3072
	ds_read_b128 v[146:149], v243
	ds_read_b128 v[150:153], v243 offset:1024
	ds_read_b128 v[164:167], v243 offset:2048
	ds_read_b128 v[168:171], v243 offset:3072
	s_add_u32 s80, s78, 0xfff80080
	s_addc_u32 s81, s79, -1
	s_cmp_eq_u32 s52, 28
	s_cselect_b32 s83, s25, s81
	s_cselect_b32 s82, s27, s80
	s_cselect_b32 s81, s23, s51
	s_cselect_b32 s80, s37, s47
	s_add_i32 m0, s7, 0xc000
	ds_read_b128 v[172:175], v179
	ds_read_b128 v[180:183], v179 offset:1024
	ds_read_b128 v[184:187], v179 offset:2048
	ds_read_b128 v[188:191], v179 offset:3072
	ds_read_b128 v[192:195], v179 offset:4096
	ds_read_b128 v[196:199], v179 offset:5120
	ds_read_b128 v[200:203], v179 offset:6144
	ds_read_b128 v[208:211], v179 offset:7168
	global_load_lds_dwordx4 v160, s[78:79]
	s_add_i32 m0, s7, 0xe000
	s_nop 0
	global_load_lds_dwordx4 v162, s[78:79]
	s_waitcnt vmcnt(8)
	s_waitcnt lgkmcnt(0)
	s_barrier
	v_mfma_f32_16x16x32_bf16 v[126:129], v[130:133], v[172:175], v[126:129]
	v_mfma_f32_16x16x32_bf16 v[122:125], v[138:141], v[172:175], v[122:125]
	v_mfma_f32_16x16x32_bf16 v[110:113], v[130:133], v[184:187], v[110:113]
	v_mfma_f32_16x16x32_bf16 v[106:109], v[138:141], v[184:187], v[106:109]
	v_mfma_f32_16x16x32_bf16 v[94:97], v[130:133], v[192:195], v[94:97]
	v_mfma_f32_16x16x32_bf16 v[90:93], v[138:141], v[192:195], v[90:93]
	v_mfma_f32_16x16x32_bf16 v[78:81], v[130:133], v[200:203], v[78:81]
	v_mfma_f32_16x16x32_bf16 v[74:77], v[138:141], v[200:203], v[74:77]
	v_mfma_f32_16x16x32_bf16 v[126:129], v[134:137], v[180:183], v[126:129]
	v_mfma_f32_16x16x32_bf16 v[122:125], v[142:145], v[180:183], v[122:125]
	v_mfma_f32_16x16x32_bf16 v[110:113], v[134:137], v[188:191], v[110:113]
	v_mfma_f32_16x16x32_bf16 v[106:109], v[142:145], v[188:191], v[106:109]
	v_mfma_f32_16x16x32_bf16 v[94:97], v[134:137], v[196:199], v[94:97]
	v_mfma_f32_16x16x32_bf16 v[90:93], v[142:145], v[196:199], v[90:93]
	v_mfma_f32_16x16x32_bf16 v[78:81], v[134:137], v[208:211], v[78:81]
	v_mfma_f32_16x16x32_bf16 v[74:77], v[142:145], v[208:211], v[74:77]
	v_mfma_f32_16x16x32_bf16 v[118:121], v[146:149], v[172:175], v[118:121]
	v_mfma_f32_16x16x32_bf16 v[114:117], v[164:167], v[172:175], v[114:117]
	v_mfma_f32_16x16x32_bf16 v[102:105], v[146:149], v[184:187], v[102:105]
	v_mfma_f32_16x16x32_bf16 v[98:101], v[164:167], v[184:187], v[98:101]
	v_mfma_f32_16x16x32_bf16 v[86:89], v[146:149], v[192:195], v[86:89]
	v_mfma_f32_16x16x32_bf16 v[82:85], v[164:167], v[192:195], v[82:85]
	v_mfma_f32_16x16x32_bf16 v[70:73], v[146:149], v[200:203], v[70:73]
	v_mfma_f32_16x16x32_bf16 v[66:69], v[164:167], v[200:203], v[66:69]
	v_mfma_f32_16x16x32_bf16 v[118:121], v[150:153], v[180:183], v[118:121]
	v_mfma_f32_16x16x32_bf16 v[114:117], v[168:171], v[180:183], v[114:117]
	v_mfma_f32_16x16x32_bf16 v[102:105], v[150:153], v[188:191], v[102:105]
	v_mfma_f32_16x16x32_bf16 v[98:101], v[168:171], v[188:191], v[98:101]
	v_mfma_f32_16x16x32_bf16 v[86:89], v[150:153], v[196:199], v[86:89]
	v_mfma_f32_16x16x32_bf16 v[82:85], v[168:171], v[196:199], v[82:85]
	v_mfma_f32_16x16x32_bf16 v[70:73], v[150:153], v[208:211], v[70:73]
	v_mfma_f32_16x16x32_bf16 v[66:69], v[168:171], v[208:211], v[66:69]
	s_barrier
	s_add_i32 s84, s88, s6
	s_mov_b32 m0, s84
	ds_read_b128 v[172:175], v179 offset:16384
	ds_read_b128 v[180:183], v179 offset:17408
	ds_read_b128 v[184:187], v179 offset:18432
	ds_read_b128 v[188:191], v179 offset:19456
	ds_read_b128 v[192:195], v179 offset:20480
	ds_read_b128 v[196:199], v179 offset:21504
	ds_read_b128 v[200:203], v179 offset:22528
	ds_read_b128 v[208:211], v179 offset:23552
	global_load_lds_dwordx4 v0, s[80:81]
	s_add_i32 m0, s84, 0x2000
	s_add_u32 s84, s80, 0x80000
	s_addc_u32 s85, s81, 0
	s_add_i32 s86, s89, s6
	global_load_lds_dwordx4 v158, s[80:81]
	s_mov_b32 m0, s86
	s_nop 0
	global_load_lds_dwordx4 v0, s[84:85]
	s_add_i32 m0, s86, 0x2000
	s_nop 0
	global_load_lds_dwordx4 v158, s[84:85]
	s_mov_b32 m0, s7
	s_nop 0
	global_load_lds_dwordx4 v154, s[82:83]
	s_mov_b32 m0, s8
	s_nop 0
	global_load_lds_dwordx4 v156, s[82:83]
	s_waitcnt vmcnt(8)
	s_waitcnt lgkmcnt(0)
	s_barrier
	v_mfma_f32_16x16x32_bf16 v[62:65], v[130:133], v[172:175], v[62:65]
	v_mfma_f32_16x16x32_bf16 v[58:61], v[138:141], v[172:175], v[58:61]
	v_mfma_f32_16x16x32_bf16 v[46:49], v[130:133], v[184:187], v[46:49]
	v_mfma_f32_16x16x32_bf16 v[42:45], v[138:141], v[184:187], v[42:45]
	v_mfma_f32_16x16x32_bf16 v[30:33], v[130:133], v[192:195], v[30:33]
	v_mfma_f32_16x16x32_bf16 v[26:29], v[138:141], v[192:195], v[26:29]
	v_mfma_f32_16x16x32_bf16 v[14:17], v[130:133], v[200:203], v[14:17]
	v_mfma_f32_16x16x32_bf16 v[10:13], v[138:141], v[200:203], v[10:13]
	v_mfma_f32_16x16x32_bf16 v[62:65], v[134:137], v[180:183], v[62:65]
	v_mfma_f32_16x16x32_bf16 v[58:61], v[142:145], v[180:183], v[58:61]
	v_mfma_f32_16x16x32_bf16 v[46:49], v[134:137], v[188:191], v[46:49]
	v_mfma_f32_16x16x32_bf16 v[42:45], v[142:145], v[188:191], v[42:45]
	v_mfma_f32_16x16x32_bf16 v[30:33], v[134:137], v[196:199], v[30:33]
	v_mfma_f32_16x16x32_bf16 v[26:29], v[142:145], v[196:199], v[26:29]
	v_mfma_f32_16x16x32_bf16 v[14:17], v[134:137], v[208:211], v[14:17]
	v_mfma_f32_16x16x32_bf16 v[10:13], v[142:145], v[208:211], v[10:13]
	v_mfma_f32_16x16x32_bf16 v[54:57], v[146:149], v[172:175], v[54:57]
	v_mfma_f32_16x16x32_bf16 v[50:53], v[164:167], v[172:175], v[50:53]
	v_mfma_f32_16x16x32_bf16 v[38:41], v[146:149], v[184:187], v[38:41]
	v_mfma_f32_16x16x32_bf16 v[34:37], v[164:167], v[184:187], v[34:37]
	v_mfma_f32_16x16x32_bf16 v[22:25], v[146:149], v[192:195], v[22:25]
	v_mfma_f32_16x16x32_bf16 v[18:21], v[164:167], v[192:195], v[18:21]
	v_mfma_f32_16x16x32_bf16 v[6:9], v[146:149], v[200:203], v[6:9]
	v_mfma_f32_16x16x32_bf16 v[2:5], v[164:167], v[200:203], v[2:5]
	v_mfma_f32_16x16x32_bf16 v[54:57], v[150:153], v[180:183], v[54:57]
	v_mfma_f32_16x16x32_bf16 v[50:53], v[168:171], v[180:183], v[50:53]
	v_mfma_f32_16x16x32_bf16 v[38:41], v[150:153], v[188:191], v[38:41]
	v_mfma_f32_16x16x32_bf16 v[34:37], v[168:171], v[188:191], v[34:37]
	v_mfma_f32_16x16x32_bf16 v[22:25], v[150:153], v[196:199], v[22:25]
	v_mfma_f32_16x16x32_bf16 v[18:21], v[168:171], v[196:199], v[18:21]
	v_mfma_f32_16x16x32_bf16 v[6:9], v[150:153], v[208:211], v[6:9]
	v_mfma_f32_16x16x32_bf16 v[2:5], v[168:171], v[208:211], v[2:5]
	s_barrier
; #define PG8_STAGE(bufoff, gbase, voff) do { _Pragma("unroll") for (int _i = 0; _i < 2; ++_i) \
;         __builtin_amdgcn_global_load_lds((const unsigned*)((const char*)(gbase) + (voff)[_i]), (PG8_LAS unsigned*)(lds + (bufoff) + ldsw + _i * 8192), 16, 0, 0); } while (0)
; #define PG8_LDA(dst, b, h) do { _Pragma("unroll") for (int m = 0; m < 4; ++m) _Pragma("unroll") for (int k = 0; k < 2; ++k) dst[m][k] = *(const PG8_LAS bf16x8*)(lds + PG8_SA(b, h) + aoff + m * 2048 + k * 1024); } while (0)
; #define PG8_LDB(dst, b, h) do { _Pragma("unroll") for (int n = 0; n < 2; ++n) _Pragma("unroll") for (int k = 0; k < 2; ++k) dst[n][k] = *(const PG8_LAS bf16x8*)(lds + PG8_SB(b, h) + boff + n * 2048 + k * 1024); } while (0)
; #define PG8_MMA(ai, bj, At, Bt) do { __builtin_amdgcn_s_setprio(1); _Pragma("unroll") for (int m = 0; m < 4; ++m) _Pragma("unroll") for (int n = 0; n < 2; ++n) _Pragma("unroll") for (int k = 0; k < 2; ++k) \
;         acc[ai][bj][m][n] = __builtin_amdgcn_mfma_f32_16x16x32_bf16(Bt[n][k], At[m][k], acc[ai][bj][m][n], 0, 0, 0); __builtin_amdgcn_s_setprio(0); } while (0)
; #define PG8_WAIT_V(n) asm volatile("s_waitcnt vmcnt(" #n ")" ::: "memory")
; #define PG8_WAIT_L(n) asm volatile("s_waitcnt lgkmcnt(" #n ")" ::: "memory")
; #define PG8_BAR __builtin_amdgcn_s_barrier()
; #define PG8_SCHED __builtin_amdgcn_sched_barrier(0)
; template <class Epi, class Sched, bool ALIGN_EPI = false, bool SP2 = false>
; __device__ __forceinline__ void gemm_phase(PG8_LAS unsigned char* lds, const Gemm g, const Sched& S, const Epi& E) {
;     ...
;             PG8_LDB(B0, 1, 0); PG8_LDB(B1, 1, 1); PG8_SCHED; PG8_LDA(At, 1, 0); PG8_STAGE(PG8_SA(0, 1), a2 + hstep, voffA);
;             PG8_WAIT_V(8); PG8_WAIT_L(0); PG8_BAR; PG8_MMA(0, 0, At, B0); PG8_MMA(0, 1, At, B1); PG8_BAR; PG8_SCHED;
;             PG8_LDA(At, 1, 1); PG8_STAGE(PG8_SB(1, 0), b3, voffB); PG8_STAGE(PG8_SB(1, 1), b3 + hstep, voffB); PG8_STAGE(PG8_SA(1, 0), a3, voffA);
;             PG8_WAIT_V(8); PG8_WAIT_L(0); PG8_BAR; PG8_MMA(1, 0, At, B0); PG8_MMA(1, 1, At, B1); PG8_BAR; PG8_SCHED;
;     ...
;         if constexpr (ALIGN_EPI) { if (wr == 0) PG8_BAR; }
	ds_read_b128 v[130:133], v244
	ds_read_b128 v[134:137], v244 offset:1024
	ds_read_b128 v[138:141], v244 offset:2048
	ds_read_b128 v[142:145], v244 offset:3072
	ds_read_b128 v[146:149], v245
	ds_read_b128 v[150:153], v245 offset:1024
	ds_read_b128 v[164:167], v245 offset:2048
	ds_read_b128 v[168:171], v245 offset:3072
	s_add_u32 s84, s82, 0x80000
	s_addc_u32 s85, s83, 0
	s_mov_b32 m0, s9
	ds_read_b128 v[172:175], v179 offset:32768
	ds_read_b128 v[180:183], v179 offset:33792
	ds_read_b128 v[184:187], v179 offset:34816
	ds_read_b128 v[188:191], v179 offset:35840
	ds_read_b128 v[192:195], v179 offset:36864
	ds_read_b128 v[196:199], v179 offset:37888
	ds_read_b128 v[200:203], v179 offset:38912
	ds_read_b128 v[208:211], v179 offset:39936
	global_load_lds_dwordx4 v154, s[84:85]
	s_mov_b32 m0, s10
	s_nop 0
	global_load_lds_dwordx4 v156, s[84:85]
	s_waitcnt vmcnt(8)
	s_waitcnt lgkmcnt(0)
	s_barrier
	v_mfma_f32_16x16x32_bf16 v[126:129], v[130:133], v[172:175], v[126:129]
	v_mfma_f32_16x16x32_bf16 v[122:125], v[138:141], v[172:175], v[122:125]
	v_mfma_f32_16x16x32_bf16 v[110:113], v[130:133], v[184:187], v[110:113]
	v_mfma_f32_16x16x32_bf16 v[106:109], v[138:141], v[184:187], v[106:109]
	v_mfma_f32_16x16x32_bf16 v[94:97], v[130:133], v[192:195], v[94:97]
	v_mfma_f32_16x16x32_bf16 v[90:93], v[138:141], v[192:195], v[90:93]
	v_mfma_f32_16x16x32_bf16 v[78:81], v[130:133], v[200:203], v[78:81]
	v_mfma_f32_16x16x32_bf16 v[74:77], v[138:141], v[200:203], v[74:77]
	v_mfma_f32_16x16x32_bf16 v[126:129], v[134:137], v[180:183], v[126:129]
	v_mfma_f32_16x16x32_bf16 v[122:125], v[142:145], v[180:183], v[122:125]
	v_mfma_f32_16x16x32_bf16 v[110:113], v[134:137], v[188:191], v[110:113]
	v_mfma_f32_16x16x32_bf16 v[106:109], v[142:145], v[188:191], v[106:109]
	v_mfma_f32_16x16x32_bf16 v[94:97], v[134:137], v[196:199], v[94:97]
	v_mfma_f32_16x16x32_bf16 v[90:93], v[142:145], v[196:199], v[90:93]
	v_mfma_f32_16x16x32_bf16 v[78:81], v[134:137], v[208:211], v[78:81]
	v_mfma_f32_16x16x32_bf16 v[74:77], v[142:145], v[208:211], v[74:77]
	v_mfma_f32_16x16x32_bf16 v[118:121], v[146:149], v[172:175], v[118:121]
	v_mfma_f32_16x16x32_bf16 v[114:117], v[164:167], v[172:175], v[114:117]
	v_mfma_f32_16x16x32_bf16 v[102:105], v[146:149], v[184:187], v[102:105]
	v_mfma_f32_16x16x32_bf16 v[98:101], v[164:167], v[184:187], v[98:101]
	v_mfma_f32_16x16x32_bf16 v[86:89], v[146:149], v[192:195], v[86:89]
	v_mfma_f32_16x16x32_bf16 v[82:85], v[164:167], v[192:195], v[82:85]
	v_mfma_f32_16x16x32_bf16 v[70:73], v[146:149], v[200:203], v[70:73]
	v_mfma_f32_16x16x32_bf16 v[66:69], v[164:167], v[200:203], v[66:69]
	v_mfma_f32_16x16x32_bf16 v[118:121], v[150:153], v[180:183], v[118:121]
	v_mfma_f32_16x16x32_bf16 v[114:117], v[168:171], v[180:183], v[114:117]
	v_mfma_f32_16x16x32_bf16 v[102:105], v[150:153], v[188:191], v[102:105]
	v_mfma_f32_16x16x32_bf16 v[98:101], v[168:171], v[188:191], v[98:101]
	v_mfma_f32_16x16x32_bf16 v[86:89], v[150:153], v[196:199], v[86:89]
	v_mfma_f32_16x16x32_bf16 v[82:85], v[168:171], v[196:199], v[82:85]
	v_mfma_f32_16x16x32_bf16 v[70:73], v[150:153], v[208:211], v[70:73]
	v_mfma_f32_16x16x32_bf16 v[66:69], v[168:171], v[208:211], v[66:69]
	s_barrier
	s_add_i32 vcc_lo, s90, s6
	s_add_u32 s84, s80, 0x80
	s_addc_u32 s85, s81, 0
	s_mov_b32 m0, vcc_lo
	ds_read_b128 v[172:175], v179 offset:49152
	ds_read_b128 v[180:183], v179 offset:50176
	ds_read_b128 v[184:187], v179 offset:51200
	ds_read_b128 v[188:191], v179 offset:52224
	ds_read_b128 v[192:195], v179 offset:53248
	ds_read_b128 v[196:199], v179 offset:54272
	ds_read_b128 v[200:203], v179 offset:55296
	ds_read_b128 v[208:211], v179 offset:56320
	global_load_lds_dwordx4 v0, s[84:85]
	s_add_i32 m0, vcc_lo, 0x2000
	s_add_i32 vcc_lo, s6, 0x1c000
	global_load_lds_dwordx4 v158, s[84:85]
	s_add_u32 s80, s80, 0x80080
	s_addc_u32 s81, s81, 0
	s_mov_b32 m0, vcc_lo
	s_nop 0
	global_load_lds_dwordx4 v0, s[80:81]
	s_add_i32 m0, vcc_lo, 0x2000
	s_nop 0
	global_load_lds_dwordx4 v158, s[80:81]
	s_add_u32 s84, s82, 0x80
	s_addc_u32 s85, s83, 0
	s_mov_b32 m0, s12
	s_nop 0
	global_load_lds_dwordx4 v154, s[84:85]
	s_mov_b32 m0, s13
	s_nop 0
	global_load_lds_dwordx4 v156, s[84:85]
	s_waitcnt vmcnt(8)
	s_waitcnt lgkmcnt(0)
	s_barrier
	v_mfma_f32_16x16x32_bf16 v[62:65], v[130:133], v[172:175], v[62:65]
	v_mfma_f32_16x16x32_bf16 v[58:61], v[138:141], v[172:175], v[58:61]
	v_mfma_f32_16x16x32_bf16 v[46:49], v[130:133], v[184:187], v[46:49]
	v_mfma_f32_16x16x32_bf16 v[42:45], v[138:141], v[184:187], v[42:45]
	v_mfma_f32_16x16x32_bf16 v[30:33], v[130:133], v[192:195], v[30:33]
	v_mfma_f32_16x16x32_bf16 v[26:29], v[138:141], v[192:195], v[26:29]
	v_mfma_f32_16x16x32_bf16 v[14:17], v[130:133], v[200:203], v[14:17]
	v_mfma_f32_16x16x32_bf16 v[10:13], v[138:141], v[200:203], v[10:13]
	v_mfma_f32_16x16x32_bf16 v[62:65], v[134:137], v[180:183], v[62:65]
	v_mfma_f32_16x16x32_bf16 v[58:61], v[142:145], v[180:183], v[58:61]
	v_mfma_f32_16x16x32_bf16 v[46:49], v[134:137], v[188:191], v[46:49]
	v_mfma_f32_16x16x32_bf16 v[42:45], v[142:145], v[188:191], v[42:45]
	v_mfma_f32_16x16x32_bf16 v[30:33], v[134:137], v[196:199], v[30:33]
	v_mfma_f32_16x16x32_bf16 v[26:29], v[142:145], v[196:199], v[26:29]
	v_mfma_f32_16x16x32_bf16 v[14:17], v[134:137], v[208:211], v[14:17]
	v_mfma_f32_16x16x32_bf16 v[10:13], v[142:145], v[208:211], v[10:13]
	v_mfma_f32_16x16x32_bf16 v[54:57], v[146:149], v[172:175], v[54:57]
	v_mfma_f32_16x16x32_bf16 v[50:53], v[164:167], v[172:175], v[50:53]
	v_mfma_f32_16x16x32_bf16 v[38:41], v[146:149], v[184:187], v[38:41]
	v_mfma_f32_16x16x32_bf16 v[34:37], v[164:167], v[184:187], v[34:37]
	v_mfma_f32_16x16x32_bf16 v[22:25], v[146:149], v[192:195], v[22:25]
	v_mfma_f32_16x16x32_bf16 v[18:21], v[164:167], v[192:195], v[18:21]
	v_mfma_f32_16x16x32_bf16 v[6:9], v[146:149], v[200:203], v[6:9]
	v_mfma_f32_16x16x32_bf16 v[2:5], v[164:167], v[200:203], v[2:5]
	v_mfma_f32_16x16x32_bf16 v[54:57], v[150:153], v[180:183], v[54:57]
	v_mfma_f32_16x16x32_bf16 v[50:53], v[168:171], v[180:183], v[50:53]
	v_mfma_f32_16x16x32_bf16 v[38:41], v[150:153], v[188:191], v[38:41]
	v_mfma_f32_16x16x32_bf16 v[34:37], v[168:171], v[188:191], v[34:37]
	v_mfma_f32_16x16x32_bf16 v[22:25], v[150:153], v[196:199], v[22:25]
	v_mfma_f32_16x16x32_bf16 v[18:21], v[168:171], v[196:199], v[18:21]
	v_mfma_f32_16x16x32_bf16 v[6:9], v[150:153], v[208:211], v[6:9]
	v_mfma_f32_16x16x32_bf16 v[2:5], v[168:171], v[208:211], v[2:5]
	s_add_i32 s52, s52, 2
	s_add_u32 s78, s78, 0x100
	s_addc_u32 s79, s79, 0
	s_add_u32 s47, s47, 0x100
	s_addc_u32 s51, s51, 0
	s_cmp_gt_u32 s52, 29
	s_barrier
	s_cbranch_scc0 .LBB0_180
	s_and_b64 vcc, exec, s[18:19]
	s_cbranch_vccz .LBB0_183
	s_barrier

; #define PG8_STAGE(bufoff, gbase, voff) do { _Pragma("unroll") for (int _i = 0; _i < 2; ++_i) \
;         __builtin_amdgcn_global_load_lds((const unsigned*)((const char*)(gbase) + (voff)[_i]), (PG8_LAS unsigned*)(lds + (bufoff) + ldsw + _i * 8192), 16, 0, 0); } while (0)
; #define PG8_LDA(dst, b, h) do { _Pragma("unroll") for (int m = 0; m < 4; ++m) _Pragma("unroll") for (int k = 0; k < 2; ++k) dst[m][k] = *(const PG8_LAS bf16x8*)(lds + PG8_SA(b, h) + aoff + m * 2048 + k * 1024); } while (0)
; #define PG8_LDB(dst, b, h) do { _Pragma("unroll") for (int n = 0; n < 2; ++n) _Pragma("unroll") for (int k = 0; k < 2; ++k) dst[n][k] = *(const PG8_LAS bf16x8*)(lds + PG8_SB(b, h) + boff + n * 2048 + k * 1024); } while (0)
; #define PG8_MMA(ai, bj, At, Bt) do { __builtin_amdgcn_s_setprio(1); _Pragma("unroll") for (int m = 0; m < 4; ++m) _Pragma("unroll") for (int n = 0; n < 2; ++n) _Pragma("unroll") for (int k = 0; k < 2; ++k) \
;         acc[ai][bj][m][n] = __builtin_amdgcn_mfma_f32_16x16x32_bf16(Bt[n][k], At[m][k], acc[ai][bj][m][n], 0, 0, 0); __builtin_amdgcn_s_setprio(0); } while (0)
; #define PG8_WAIT_V(n) asm volatile("s_waitcnt vmcnt(" #n ")" ::: "memory")
; #define PG8_WAIT_L(n) asm volatile("s_waitcnt lgkmcnt(" #n ")" ::: "memory")
; #define PG8_BAR __builtin_amdgcn_s_barrier()
; #define PG8_SCHED __builtin_amdgcn_sched_barrier(0)
; template <class Epi, class Sched, bool ALIGN_EPI = false, bool SP2 = false>
; __device__ __forceinline__ void gemm_phase(PG8_LAS unsigned char* lds, const Gemm g, const Sched& S, const Epi& E) {
;     ...
;             PG8_LDB(B0, 0, 0); PG8_LDB(B1, 0, 1); PG8_SCHED; PG8_LDA(At, 0, 0); PG8_STAGE(PG8_SA(1, 1), a1 + hstep, voffA);
;             PG8_WAIT_V(8); PG8_WAIT_L(0); PG8_BAR; PG8_MMA(0, 0, At, B0); PG8_MMA(0, 1, At, B1); PG8_BAR; PG8_SCHED;
;             PG8_LDA(At, 0, 1); PG8_STAGE(PG8_SB(0, 0), b2, voffB); PG8_STAGE(PG8_SB(0, 1), b2 + hstep, voffB); PG8_STAGE(PG8_SA(0, 0), a2, voffA);
;             PG8_WAIT_V(8); PG8_WAIT_L(0); PG8_BAR; PG8_MMA(1, 0, At, B0); PG8_MMA(1, 1, At, B1); PG8_BAR; PG8_SCHED;
.LBB0_214:
	ds_read_b128 v[114:117], v242
	ds_read_b128 v[118:121], v242 offset:1024
	ds_read_b128 v[130:133], v242 offset:2048
	ds_read_b128 v[134:137], v242 offset:3072
	ds_read_b128 v[146:149], v243
	ds_read_b128 v[150:153], v243 offset:1024
	ds_read_b128 v[168:171], v243 offset:2048
	ds_read_b128 v[172:175], v243 offset:3072
	s_add_u32 s40, s34, 0xfff80080
	s_addc_u32 s41, s35, -1
	s_cmp_eq_u32 s46, 28
	s_cselect_b32 s43, s15, s41
	s_cselect_b32 s42, s19, s40
	s_cselect_b32 s41, s17, s45
	s_cselect_b32 s40, s37, s44
	s_add_i32 m0, s8, 0xc000
	ds_read_b128 v[180:183], v178
	ds_read_b128 v[184:187], v178 offset:1024
	ds_read_b128 v[188:191], v178 offset:2048
	ds_read_b128 v[192:195], v178 offset:3072
	ds_read_b128 v[196:199], v178 offset:4096
	ds_read_b128 v[200:203], v178 offset:5120
	ds_read_b128 v[208:211], v178 offset:6144
	ds_read_b128 v[230:233], v178 offset:7168
	global_load_lds_dwordx4 v164, s[34:35]
	s_add_i32 m0, s8, 0xe000
	s_nop 0
	global_load_lds_dwordx4 v166, s[34:35]
	s_waitcnt vmcnt(8)
	s_waitcnt lgkmcnt(0)
	s_barrier
	v_mfma_f32_16x16x32_bf16 v[142:145], v[114:117], v[180:183], v[142:145]
	v_mfma_f32_16x16x32_bf16 v[138:141], v[130:133], v[180:183], v[138:141]
	v_mfma_f32_16x16x32_bf16 v[110:113], v[114:117], v[188:191], v[110:113]
	v_mfma_f32_16x16x32_bf16 v[106:109], v[130:133], v[188:191], v[106:109]
	v_mfma_f32_16x16x32_bf16 v[94:97], v[114:117], v[196:199], v[94:97]
	v_mfma_f32_16x16x32_bf16 v[90:93], v[130:133], v[196:199], v[90:93]
	v_mfma_f32_16x16x32_bf16 v[78:81], v[114:117], v[208:211], v[78:81]
	v_mfma_f32_16x16x32_bf16 v[74:77], v[130:133], v[208:211], v[74:77]
	v_mfma_f32_16x16x32_bf16 v[142:145], v[118:121], v[184:187], v[142:145]
	v_mfma_f32_16x16x32_bf16 v[138:141], v[134:137], v[184:187], v[138:141]
	v_mfma_f32_16x16x32_bf16 v[110:113], v[118:121], v[192:195], v[110:113]
	v_mfma_f32_16x16x32_bf16 v[106:109], v[134:137], v[192:195], v[106:109]
	v_mfma_f32_16x16x32_bf16 v[94:97], v[118:121], v[200:203], v[94:97]
	v_mfma_f32_16x16x32_bf16 v[90:93], v[134:137], v[200:203], v[90:93]
	v_mfma_f32_16x16x32_bf16 v[78:81], v[118:121], v[230:233], v[78:81]
	v_mfma_f32_16x16x32_bf16 v[74:77], v[134:137], v[230:233], v[74:77]
	v_mfma_f32_16x16x32_bf16 v[126:129], v[146:149], v[180:183], v[126:129]
	v_mfma_f32_16x16x32_bf16 v[122:125], v[168:171], v[180:183], v[122:125]
	v_mfma_f32_16x16x32_bf16 v[102:105], v[146:149], v[188:191], v[102:105]
	v_mfma_f32_16x16x32_bf16 v[98:101], v[168:171], v[188:191], v[98:101]
	v_mfma_f32_16x16x32_bf16 v[86:89], v[146:149], v[196:199], v[86:89]
	v_mfma_f32_16x16x32_bf16 v[82:85], v[168:171], v[196:199], v[82:85]
	v_mfma_f32_16x16x32_bf16 v[70:73], v[146:149], v[208:211], v[70:73]
	v_mfma_f32_16x16x32_bf16 v[66:69], v[168:171], v[208:211], v[66:69]
	v_mfma_f32_16x16x32_bf16 v[126:129], v[150:153], v[184:187], v[126:129]
	v_mfma_f32_16x16x32_bf16 v[122:125], v[172:175], v[184:187], v[122:125]
	v_mfma_f32_16x16x32_bf16 v[102:105], v[150:153], v[192:195], v[102:105]
	v_mfma_f32_16x16x32_bf16 v[98:101], v[172:175], v[192:195], v[98:101]
	v_mfma_f32_16x16x32_bf16 v[86:89], v[150:153], v[200:203], v[86:89]
	v_mfma_f32_16x16x32_bf16 v[82:85], v[172:175], v[200:203], v[82:85]
	v_mfma_f32_16x16x32_bf16 v[70:73], v[150:153], v[230:233], v[70:73]
	v_mfma_f32_16x16x32_bf16 v[66:69], v[172:175], v[230:233], v[66:69]
	s_barrier
	s_add_i32 s47, s88, s6
	s_mov_b32 m0, s47
	ds_read_b128 v[180:183], v178 offset:16384
	ds_read_b128 v[184:187], v178 offset:17408
	ds_read_b128 v[188:191], v178 offset:18432
	ds_read_b128 v[192:195], v178 offset:19456
	ds_read_b128 v[196:199], v178 offset:20480
	ds_read_b128 v[200:203], v178 offset:21504
	ds_read_b128 v[208:211], v178 offset:22528
	ds_read_b128 v[230:233], v178 offset:23552
	global_load_lds_dwordx4 v0, s[40:41]
	s_add_i32 m0, s47, 0x2000
	s_add_u32 s50, s40, 0x80000
	s_addc_u32 s51, s41, 0
	s_add_i32 s47, s89, s6
	global_load_lds_dwordx4 v154, s[40:41]
	s_mov_b32 m0, s47
	s_nop 0
	global_load_lds_dwordx4 v0, s[50:51]
	s_add_i32 m0, s47, 0x2000
	s_nop 0
	global_load_lds_dwordx4 v154, s[50:51]
	s_mov_b32 m0, s8
	s_nop 0
	global_load_lds_dwordx4 v158, s[42:43]
	s_mov_b32 m0, s9
	s_nop 0
	global_load_lds_dwordx4 v156, s[42:43]
	s_waitcnt vmcnt(8)
	s_waitcnt lgkmcnt(0)
	s_barrier
	v_mfma_f32_16x16x32_bf16 v[62:65], v[114:117], v[180:183], v[62:65]
	v_mfma_f32_16x16x32_bf16 v[58:61], v[130:133], v[180:183], v[58:61]
	v_mfma_f32_16x16x32_bf16 v[46:49], v[114:117], v[188:191], v[46:49]
	v_mfma_f32_16x16x32_bf16 v[42:45], v[130:133], v[188:191], v[42:45]
	v_mfma_f32_16x16x32_bf16 v[30:33], v[114:117], v[196:199], v[30:33]
	v_mfma_f32_16x16x32_bf16 v[26:29], v[130:133], v[196:199], v[26:29]
	v_mfma_f32_16x16x32_bf16 v[14:17], v[114:117], v[208:211], v[14:17]
	v_mfma_f32_16x16x32_bf16 v[10:13], v[130:133], v[208:211], v[10:13]
	v_mfma_f32_16x16x32_bf16 v[62:65], v[118:121], v[184:187], v[62:65]
	v_mfma_f32_16x16x32_bf16 v[58:61], v[134:137], v[184:187], v[58:61]
	v_mfma_f32_16x16x32_bf16 v[46:49], v[118:121], v[192:195], v[46:49]
	v_mfma_f32_16x16x32_bf16 v[42:45], v[134:137], v[192:195], v[42:45]
	v_mfma_f32_16x16x32_bf16 v[30:33], v[118:121], v[200:203], v[30:33]
	v_mfma_f32_16x16x32_bf16 v[26:29], v[134:137], v[200:203], v[26:29]
	v_mfma_f32_16x16x32_bf16 v[14:17], v[118:121], v[230:233], v[14:17]
	v_mfma_f32_16x16x32_bf16 v[10:13], v[134:137], v[230:233], v[10:13]
	v_mfma_f32_16x16x32_bf16 v[54:57], v[146:149], v[180:183], v[54:57]
	v_mfma_f32_16x16x32_bf16 v[50:53], v[168:171], v[180:183], v[50:53]
	v_mfma_f32_16x16x32_bf16 v[38:41], v[146:149], v[188:191], v[38:41]
	v_mfma_f32_16x16x32_bf16 v[34:37], v[168:171], v[188:191], v[34:37]
	v_mfma_f32_16x16x32_bf16 v[22:25], v[146:149], v[196:199], v[22:25]
	v_mfma_f32_16x16x32_bf16 v[18:21], v[168:171], v[196:199], v[18:21]
	v_mfma_f32_16x16x32_bf16 v[6:9], v[146:149], v[208:211], v[6:9]
	v_mfma_f32_16x16x32_bf16 v[2:5], v[168:171], v[208:211], v[2:5]
	v_mfma_f32_16x16x32_bf16 v[54:57], v[150:153], v[184:187], v[54:57]
	v_mfma_f32_16x16x32_bf16 v[50:53], v[172:175], v[184:187], v[50:53]
	v_mfma_f32_16x16x32_bf16 v[38:41], v[150:153], v[192:195], v[38:41]
	v_mfma_f32_16x16x32_bf16 v[34:37], v[172:175], v[192:195], v[34:37]
	v_mfma_f32_16x16x32_bf16 v[22:25], v[150:153], v[200:203], v[22:25]
	v_mfma_f32_16x16x32_bf16 v[18:21], v[172:175], v[200:203], v[18:21]
	v_mfma_f32_16x16x32_bf16 v[6:9], v[150:153], v[230:233], v[6:9]
	v_mfma_f32_16x16x32_bf16 v[2:5], v[172:175], v[230:233], v[2:5]
	s_barrier
; #define PG8_STAGE(bufoff, gbase, voff) do { _Pragma("unroll") for (int _i = 0; _i < 2; ++_i) \
;         __builtin_amdgcn_global_load_lds((const unsigned*)((const char*)(gbase) + (voff)[_i]), (PG8_LAS unsigned*)(lds + (bufoff) + ldsw + _i * 8192), 16, 0, 0); } while (0)
; #define PG8_LDA(dst, b, h) do { _Pragma("unroll") for (int m = 0; m < 4; ++m) _Pragma("unroll") for (int k = 0; k < 2; ++k) dst[m][k] = *(const PG8_LAS bf16x8*)(lds + PG8_SA(b, h) + aoff + m * 2048 + k * 1024); } while (0)
; #define PG8_LDB(dst, b, h) do { _Pragma("unroll") for (int n = 0; n < 2; ++n) _Pragma("unroll") for (int k = 0; k < 2; ++k) dst[n][k] = *(const PG8_LAS bf16x8*)(lds + PG8_SB(b, h) + boff + n * 2048 + k * 1024); } while (0)
; #define PG8_MMA(ai, bj, At, Bt) do { __builtin_amdgcn_s_setprio(1); _Pragma("unroll") for (int m = 0; m < 4; ++m) _Pragma("unroll") for (int n = 0; n < 2; ++n) _Pragma("unroll") for (int k = 0; k < 2; ++k) \
;         acc[ai][bj][m][n] = __builtin_amdgcn_mfma_f32_16x16x32_bf16(Bt[n][k], At[m][k], acc[ai][bj][m][n], 0, 0, 0); __builtin_amdgcn_s_setprio(0); } while (0)
; #define PG8_WAIT_V(n) asm volatile("s_waitcnt vmcnt(" #n ")" ::: "memory")
; #define PG8_WAIT_L(n) asm volatile("s_waitcnt lgkmcnt(" #n ")" ::: "memory")
; #define PG8_BAR __builtin_amdgcn_s_barrier()
; #define PG8_SCHED __builtin_amdgcn_sched_barrier(0)
; template <class Epi, class Sched, bool ALIGN_EPI = false, bool SP2 = false>
; __device__ __forceinline__ void gemm_phase(PG8_LAS unsigned char* lds, const Gemm g, const Sched& S, const Epi& E) {
;     ...
;         for (int t = 0; t < nt; t += 2) {
;     ...
;             PG8_LDB(B0, 1, 0); PG8_LDB(B1, 1, 1); PG8_SCHED; PG8_LDA(At, 1, 0); PG8_STAGE(PG8_SA(0, 1), a2 + hstep, voffA);
;             PG8_WAIT_V(8); PG8_WAIT_L(0); PG8_BAR; PG8_MMA(0, 0, At, B0); PG8_MMA(0, 1, At, B1); PG8_BAR; PG8_SCHED;
;             PG8_LDA(At, 1, 1); PG8_STAGE(PG8_SB(1, 0), b3, voffB); PG8_STAGE(PG8_SB(1, 1), b3 + hstep, voffB); PG8_STAGE(PG8_SA(1, 0), a3, voffA);
;             PG8_WAIT_V(8); PG8_WAIT_L(0); PG8_BAR; PG8_MMA(1, 0, At, B0); PG8_MMA(1, 1, At, B1); PG8_BAR; PG8_SCHED;
	s_add_i32 s47, 0, 0x1c000
	ds_read_b128 v[114:117], v244
	ds_read_b128 v[118:121], v244 offset:1024
	ds_read_b128 v[130:133], v244 offset:2048
	ds_read_b128 v[134:137], v244 offset:3072
	ds_read_b128 v[146:149], v245
	ds_read_b128 v[150:153], v245 offset:1024
	ds_read_b128 v[168:171], v245 offset:2048
	ds_read_b128 v[172:175], v245 offset:3072
	s_add_u32 s50, s42, 0x80000
	s_addc_u32 s51, s43, 0
	s_mov_b32 m0, s10
	ds_read_b128 v[180:183], v178 offset:32768
	ds_read_b128 v[184:187], v178 offset:33792
	ds_read_b128 v[188:191], v178 offset:34816
	ds_read_b128 v[192:195], v178 offset:35840
	ds_read_b128 v[196:199], v178 offset:36864
	ds_read_b128 v[200:203], v178 offset:37888
	ds_read_b128 v[208:211], v178 offset:38912
	ds_read_b128 v[230:233], v178 offset:39936
	global_load_lds_dwordx4 v158, s[50:51]
	s_mov_b32 m0, s11
	s_nop 0
	global_load_lds_dwordx4 v156, s[50:51]
	s_waitcnt vmcnt(8)
	s_waitcnt lgkmcnt(0)
	s_barrier
	v_mfma_f32_16x16x32_bf16 v[142:145], v[114:117], v[180:183], v[142:145]
	v_mfma_f32_16x16x32_bf16 v[138:141], v[130:133], v[180:183], v[138:141]
	v_mfma_f32_16x16x32_bf16 v[110:113], v[114:117], v[188:191], v[110:113]
	v_mfma_f32_16x16x32_bf16 v[106:109], v[130:133], v[188:191], v[106:109]
	v_mfma_f32_16x16x32_bf16 v[94:97], v[114:117], v[196:199], v[94:97]
	v_mfma_f32_16x16x32_bf16 v[90:93], v[130:133], v[196:199], v[90:93]
	v_mfma_f32_16x16x32_bf16 v[78:81], v[114:117], v[208:211], v[78:81]
	v_mfma_f32_16x16x32_bf16 v[74:77], v[130:133], v[208:211], v[74:77]
	v_mfma_f32_16x16x32_bf16 v[142:145], v[118:121], v[184:187], v[142:145]
	v_mfma_f32_16x16x32_bf16 v[138:141], v[134:137], v[184:187], v[138:141]
	v_mfma_f32_16x16x32_bf16 v[110:113], v[118:121], v[192:195], v[110:113]
	v_mfma_f32_16x16x32_bf16 v[106:109], v[134:137], v[192:195], v[106:109]
	v_mfma_f32_16x16x32_bf16 v[94:97], v[118:121], v[200:203], v[94:97]
	v_mfma_f32_16x16x32_bf16 v[90:93], v[134:137], v[200:203], v[90:93]
	v_mfma_f32_16x16x32_bf16 v[78:81], v[118:121], v[230:233], v[78:81]
	v_mfma_f32_16x16x32_bf16 v[74:77], v[134:137], v[230:233], v[74:77]
	v_mfma_f32_16x16x32_bf16 v[126:129], v[146:149], v[180:183], v[126:129]
	v_mfma_f32_16x16x32_bf16 v[122:125], v[168:171], v[180:183], v[122:125]
	v_mfma_f32_16x16x32_bf16 v[102:105], v[146:149], v[188:191], v[102:105]
	v_mfma_f32_16x16x32_bf16 v[98:101], v[168:171], v[188:191], v[98:101]
	v_mfma_f32_16x16x32_bf16 v[86:89], v[146:149], v[196:199], v[86:89]
	v_mfma_f32_16x16x32_bf16 v[82:85], v[168:171], v[196:199], v[82:85]
	v_mfma_f32_16x16x32_bf16 v[70:73], v[146:149], v[208:211], v[70:73]
	v_mfma_f32_16x16x32_bf16 v[66:69], v[168:171], v[208:211], v[66:69]
	v_mfma_f32_16x16x32_bf16 v[126:129], v[150:153], v[184:187], v[126:129]
	v_mfma_f32_16x16x32_bf16 v[122:125], v[172:175], v[184:187], v[122:125]
	v_mfma_f32_16x16x32_bf16 v[102:105], v[150:153], v[192:195], v[102:105]
	v_mfma_f32_16x16x32_bf16 v[98:101], v[172:175], v[192:195], v[98:101]
	v_mfma_f32_16x16x32_bf16 v[86:89], v[150:153], v[200:203], v[86:89]
	v_mfma_f32_16x16x32_bf16 v[82:85], v[172:175], v[200:203], v[82:85]
	v_mfma_f32_16x16x32_bf16 v[70:73], v[150:153], v[230:233], v[70:73]
	v_mfma_f32_16x16x32_bf16 v[66:69], v[172:175], v[230:233], v[66:69]
	s_barrier
	s_add_i32 vcc_lo, s90, s6
	s_add_u32 s50, s40, 0x80
	s_addc_u32 s51, s41, 0
	s_mov_b32 m0, vcc_lo
	ds_read_b128 v[180:183], v178 offset:49152
	ds_read_b128 v[184:187], v178 offset:50176
	ds_read_b128 v[188:191], v178 offset:51200
	ds_read_b128 v[192:195], v178 offset:52224
	ds_read_b128 v[196:199], v178 offset:53248
	ds_read_b128 v[200:203], v178 offset:54272
	ds_read_b128 v[208:211], v178 offset:55296
	ds_read_b128 v[230:233], v178 offset:56320
	global_load_lds_dwordx4 v0, s[50:51]
	s_add_i32 m0, vcc_lo, 0x2000
	s_add_i32 vcc_lo, s47, s6
	global_load_lds_dwordx4 v154, s[50:51]
	s_add_u32 s40, s40, 0x80080
	s_addc_u32 s41, s41, 0
	s_mov_b32 m0, vcc_lo
	s_nop 0
	global_load_lds_dwordx4 v0, s[40:41]
	s_add_i32 m0, vcc_lo, 0x2000
	s_nop 0
	global_load_lds_dwordx4 v154, s[40:41]
	s_add_u32 s50, s42, 0x80
	s_addc_u32 s51, s43, 0
	s_mov_b32 m0, s13
	s_nop 0
	global_load_lds_dwordx4 v158, s[50:51]
	s_mov_b32 m0, s25
	s_nop 0
	global_load_lds_dwordx4 v156, s[50:51]
	s_waitcnt vmcnt(8)
	s_waitcnt lgkmcnt(0)
	s_barrier
	v_mfma_f32_16x16x32_bf16 v[62:65], v[114:117], v[180:183], v[62:65]
	v_mfma_f32_16x16x32_bf16 v[58:61], v[130:133], v[180:183], v[58:61]
	v_mfma_f32_16x16x32_bf16 v[46:49], v[114:117], v[188:191], v[46:49]
	v_mfma_f32_16x16x32_bf16 v[42:45], v[130:133], v[188:191], v[42:45]
	v_mfma_f32_16x16x32_bf16 v[30:33], v[114:117], v[196:199], v[30:33]
	v_mfma_f32_16x16x32_bf16 v[26:29], v[130:133], v[196:199], v[26:29]
	v_mfma_f32_16x16x32_bf16 v[14:17], v[114:117], v[208:211], v[14:17]
	v_mfma_f32_16x16x32_bf16 v[10:13], v[130:133], v[208:211], v[10:13]
	v_mfma_f32_16x16x32_bf16 v[62:65], v[118:121], v[184:187], v[62:65]
	v_mfma_f32_16x16x32_bf16 v[58:61], v[134:137], v[184:187], v[58:61]
	v_mfma_f32_16x16x32_bf16 v[46:49], v[118:121], v[192:195], v[46:49]
	v_mfma_f32_16x16x32_bf16 v[42:45], v[134:137], v[192:195], v[42:45]
	v_mfma_f32_16x16x32_bf16 v[30:33], v[118:121], v[200:203], v[30:33]
	v_mfma_f32_16x16x32_bf16 v[26:29], v[134:137], v[200:203], v[26:29]
	v_mfma_f32_16x16x32_bf16 v[14:17], v[118:121], v[230:233], v[14:17]
	v_mfma_f32_16x16x32_bf16 v[10:13], v[134:137], v[230:233], v[10:13]
	v_mfma_f32_16x16x32_bf16 v[54:57], v[146:149], v[180:183], v[54:57]
	v_mfma_f32_16x16x32_bf16 v[50:53], v[168:171], v[180:183], v[50:53]
	v_mfma_f32_16x16x32_bf16 v[38:41], v[146:149], v[188:191], v[38:41]
	v_mfma_f32_16x16x32_bf16 v[34:37], v[168:171], v[188:191], v[34:37]
	v_mfma_f32_16x16x32_bf16 v[22:25], v[146:149], v[196:199], v[22:25]
	v_mfma_f32_16x16x32_bf16 v[18:21], v[168:171], v[196:199], v[18:21]
	v_mfma_f32_16x16x32_bf16 v[6:9], v[146:149], v[208:211], v[6:9]
	v_mfma_f32_16x16x32_bf16 v[2:5], v[168:171], v[208:211], v[2:5]
	v_mfma_f32_16x16x32_bf16 v[54:57], v[150:153], v[184:187], v[54:57]
	v_mfma_f32_16x16x32_bf16 v[50:53], v[172:175], v[184:187], v[50:53]
	v_mfma_f32_16x16x32_bf16 v[38:41], v[150:153], v[192:195], v[38:41]
	v_mfma_f32_16x16x32_bf16 v[34:37], v[172:175], v[192:195], v[34:37]
	v_mfma_f32_16x16x32_bf16 v[22:25], v[150:153], v[200:203], v[22:25]
	v_mfma_f32_16x16x32_bf16 v[18:21], v[172:175], v[200:203], v[18:21]
	v_mfma_f32_16x16x32_bf16 v[6:9], v[150:153], v[230:233], v[6:9]
	v_mfma_f32_16x16x32_bf16 v[2:5], v[172:175], v[230:233], v[2:5]
	s_add_i32 s46, s46, 2
	s_add_u32 s34, s34, 0x100
	s_addc_u32 s35, s35, 0
	s_add_u32 s44, s44, 0x100
	s_addc_u32 s45, s45, 0
	s_cmp_gt_u32 s46, 29
	s_barrier
	s_cbranch_scc0 .LBB0_214

; #define PG8_STAGE(bufoff, gbase, voff) do { _Pragma("unroll") for (int _i = 0; _i < 2; ++_i) \
;         __builtin_amdgcn_global_load_lds((const unsigned*)((const char*)(gbase) + (voff)[_i]), (PG8_LAS unsigned*)(lds + (bufoff) + ldsw + _i * 8192), 16, 0, 0); } while (0)
; #define PG8_LDA(dst, b, h) do { _Pragma("unroll") for (int m = 0; m < 4; ++m) _Pragma("unroll") for (int k = 0; k < 2; ++k) dst[m][k] = *(const PG8_LAS bf16x8*)(lds + PG8_SA(b, h) + aoff + m * 2048 + k * 1024); } while (0)
; #define PG8_LDB(dst, b, h) do { _Pragma("unroll") for (int n = 0; n < 2; ++n) _Pragma("unroll") for (int k = 0; k < 2; ++k) dst[n][k] = *(const PG8_LAS bf16x8*)(lds + PG8_SB(b, h) + boff + n * 2048 + k * 1024); } while (0)
; #define PG8_MMA(ai, bj, At, Bt) do { __builtin_amdgcn_s_setprio(1); _Pragma("unroll") for (int m = 0; m < 4; ++m) _Pragma("unroll") for (int n = 0; n < 2; ++n) _Pragma("unroll") for (int k = 0; k < 2; ++k) \
;         acc[ai][bj][m][n] = __builtin_amdgcn_mfma_f32_16x16x32_bf16(Bt[n][k], At[m][k], acc[ai][bj][m][n], 0, 0, 0); __builtin_amdgcn_s_setprio(0); } while (0)
; #define PG8_WAIT_V(n) asm volatile("s_waitcnt vmcnt(" #n ")" ::: "memory")
; #define PG8_WAIT_L(n) asm volatile("s_waitcnt lgkmcnt(" #n ")" ::: "memory")
; #define PG8_BAR __builtin_amdgcn_s_barrier()
; #define PG8_SCHED __builtin_amdgcn_sched_barrier(0)
; template <class Epi, class Sched, bool ALIGN_EPI = false, bool SP2 = false>
; __device__ __forceinline__ void gemm_phase(PG8_LAS unsigned char* lds, const Gemm g, const Sched& S, const Epi& E) {
;     ...
;             PG8_LDB(B0, 0, 0); PG8_LDB(B1, 0, 1); PG8_SCHED; PG8_LDA(At, 0, 0); PG8_STAGE(PG8_SA(1, 1), a1 + hstep, voffA);
;             PG8_WAIT_V(8); PG8_WAIT_L(0); PG8_BAR; PG8_MMA(0, 0, At, B0); PG8_MMA(0, 1, At, B1); PG8_BAR; PG8_SCHED;
;             PG8_LDA(At, 0, 1); PG8_STAGE(PG8_SB(0, 0), b2, voffB); PG8_STAGE(PG8_SB(0, 1), b2 + hstep, voffB); PG8_STAGE(PG8_SA(0, 0), a2, voffA);
;             PG8_WAIT_V(8); PG8_WAIT_L(0); PG8_BAR; PG8_MMA(1, 0, At, B0); PG8_MMA(1, 1, At, B1); PG8_BAR; PG8_SCHED;
.Ltail_loop:
	ds_read_b128 v[114:117], v242
	ds_read_b128 v[118:121], v242 offset:1024
	ds_read_b128 v[130:133], v242 offset:2048
	ds_read_b128 v[134:137], v242 offset:3072
	s_add_u32 s40, s34, 0xfff80080
	s_addc_u32 s41, s35, -1
	s_cmp_eq_u32 s46, 28
	s_cselect_b32 s43, s15, s41
	s_cselect_b32 s42, s19, s40
	s_cselect_b32 s41, s17, s45
	s_cselect_b32 s40, s37, s44
	s_add_i32 m0, s8, 0xc000
	ds_read_b128 v[180:183], v178
	ds_read_b128 v[184:187], v178 offset:1024
	ds_read_b128 v[188:191], v178 offset:2048
	ds_read_b128 v[192:195], v178 offset:3072
	ds_read_b128 v[196:199], v178 offset:4096
	ds_read_b128 v[200:203], v178 offset:5120
	ds_read_b128 v[208:211], v178 offset:6144
	ds_read_b128 v[230:233], v178 offset:7168
	global_load_lds_dwordx4 v164, s[34:35]
	s_add_i32 m0, s8, 0xe000
	s_nop 0
	global_load_lds_dwordx4 v166, s[34:35]
	s_waitcnt vmcnt(6)
	s_waitcnt lgkmcnt(0)
	s_barrier
	v_mfma_f32_16x16x32_bf16 v[142:145], v[114:117], v[180:183], v[142:145]
	v_mfma_f32_16x16x32_bf16 v[138:141], v[130:133], v[180:183], v[138:141]
	v_mfma_f32_16x16x32_bf16 v[110:113], v[114:117], v[188:191], v[110:113]
	v_mfma_f32_16x16x32_bf16 v[106:109], v[130:133], v[188:191], v[106:109]
	v_mfma_f32_16x16x32_bf16 v[94:97], v[114:117], v[196:199], v[94:97]
	v_mfma_f32_16x16x32_bf16 v[90:93], v[130:133], v[196:199], v[90:93]
	v_mfma_f32_16x16x32_bf16 v[78:81], v[114:117], v[208:211], v[78:81]
	v_mfma_f32_16x16x32_bf16 v[74:77], v[130:133], v[208:211], v[74:77]
	v_mfma_f32_16x16x32_bf16 v[142:145], v[118:121], v[184:187], v[142:145]
	v_mfma_f32_16x16x32_bf16 v[138:141], v[134:137], v[184:187], v[138:141]
	v_mfma_f32_16x16x32_bf16 v[110:113], v[118:121], v[192:195], v[110:113]
	v_mfma_f32_16x16x32_bf16 v[106:109], v[134:137], v[192:195], v[106:109]
	v_mfma_f32_16x16x32_bf16 v[94:97], v[118:121], v[200:203], v[94:97]
	v_mfma_f32_16x16x32_bf16 v[90:93], v[134:137], v[200:203], v[90:93]
	v_mfma_f32_16x16x32_bf16 v[78:81], v[118:121], v[230:233], v[78:81]
	v_mfma_f32_16x16x32_bf16 v[74:77], v[134:137], v[230:233], v[74:77]
	s_barrier
	s_add_i32 s47, s88, s6
	s_mov_b32 m0, s47
	ds_read_b128 v[180:183], v178 offset:16384
	ds_read_b128 v[184:187], v178 offset:17408
	ds_read_b128 v[188:191], v178 offset:18432
	ds_read_b128 v[192:195], v178 offset:19456
	ds_read_b128 v[196:199], v178 offset:20480
	ds_read_b128 v[200:203], v178 offset:21504
	ds_read_b128 v[208:211], v178 offset:22528
	ds_read_b128 v[230:233], v178 offset:23552
	global_load_lds_dwordx4 v0, s[40:41]
	s_add_i32 m0, s47, 0x2000
	s_nop 0
	global_load_lds_dwordx4 v154, s[40:41]
	s_mov_b32 m0, s8
	s_nop 0
	global_load_lds_dwordx4 v158, s[42:43]
	s_mov_b32 m0, s9
	s_nop 0
	global_load_lds_dwordx4 v156, s[42:43]
	s_waitcnt vmcnt(6)
	s_waitcnt lgkmcnt(0)
	s_barrier
	v_mfma_f32_16x16x32_bf16 v[62:65], v[114:117], v[180:183], v[62:65]
	v_mfma_f32_16x16x32_bf16 v[58:61], v[130:133], v[180:183], v[58:61]
	v_mfma_f32_16x16x32_bf16 v[46:49], v[114:117], v[188:191], v[46:49]
	v_mfma_f32_16x16x32_bf16 v[42:45], v[130:133], v[188:191], v[42:45]
	v_mfma_f32_16x16x32_bf16 v[30:33], v[114:117], v[196:199], v[30:33]
	v_mfma_f32_16x16x32_bf16 v[26:29], v[130:133], v[196:199], v[26:29]
	v_mfma_f32_16x16x32_bf16 v[14:17], v[114:117], v[208:211], v[14:17]
	v_mfma_f32_16x16x32_bf16 v[10:13], v[130:133], v[208:211], v[10:13]
	v_mfma_f32_16x16x32_bf16 v[62:65], v[118:121], v[184:187], v[62:65]
	v_mfma_f32_16x16x32_bf16 v[58:61], v[134:137], v[184:187], v[58:61]
	v_mfma_f32_16x16x32_bf16 v[46:49], v[118:121], v[192:195], v[46:49]
	v_mfma_f32_16x16x32_bf16 v[42:45], v[134:137], v[192:195], v[42:45]
	v_mfma_f32_16x16x32_bf16 v[30:33], v[118:121], v[200:203], v[30:33]
	v_mfma_f32_16x16x32_bf16 v[26:29], v[134:137], v[200:203], v[26:29]
	v_mfma_f32_16x16x32_bf16 v[14:17], v[118:121], v[230:233], v[14:17]
	v_mfma_f32_16x16x32_bf16 v[10:13], v[134:137], v[230:233], v[10:13]
	s_barrier
; #define PG8_STAGE(bufoff, gbase, voff) do { _Pragma("unroll") for (int _i = 0; _i < 2; ++_i) \
;         __builtin_amdgcn_global_load_lds((const unsigned*)((const char*)(gbase) + (voff)[_i]), (PG8_LAS unsigned*)(lds + (bufoff) + ldsw + _i * 8192), 16, 0, 0); } while (0)
; #define PG8_LDA(dst, b, h) do { _Pragma("unroll") for (int m = 0; m < 4; ++m) _Pragma("unroll") for (int k = 0; k < 2; ++k) dst[m][k] = *(const PG8_LAS bf16x8*)(lds + PG8_SA(b, h) + aoff + m * 2048 + k * 1024); } while (0)
; #define PG8_LDB(dst, b, h) do { _Pragma("unroll") for (int n = 0; n < 2; ++n) _Pragma("unroll") for (int k = 0; k < 2; ++k) dst[n][k] = *(const PG8_LAS bf16x8*)(lds + PG8_SB(b, h) + boff + n * 2048 + k * 1024); } while (0)
; #define PG8_MMA(ai, bj, At, Bt) do { __builtin_amdgcn_s_setprio(1); _Pragma("unroll") for (int m = 0; m < 4; ++m) _Pragma("unroll") for (int n = 0; n < 2; ++n) _Pragma("unroll") for (int k = 0; k < 2; ++k) \
;         acc[ai][bj][m][n] = __builtin_amdgcn_mfma_f32_16x16x32_bf16(Bt[n][k], At[m][k], acc[ai][bj][m][n], 0, 0, 0); __builtin_amdgcn_s_setprio(0); } while (0)
; #define PG8_WAIT_V(n) asm volatile("s_waitcnt vmcnt(" #n ")" ::: "memory")
; template <class Epi, class Sched, bool ALIGN_EPI = false, bool SP2 = false>
; __device__ __forceinline__ void gemm_phase(PG8_LAS unsigned char* lds, const Gemm g, const Sched& S, const Epi& E) {
;     ...
;             PG8_LDB(B0, 0, 0); PG8_LDB(B1, 0, 1); PG8_SCHED; PG8_LDA(At, 0, 0); PG8_STAGE(PG8_SA(1, 1), a1 + hstep, voffA);
;             PG8_WAIT_V(8); PG8_WAIT_L(0); PG8_BAR; PG8_MMA(0, 0, At, B0); PG8_MMA(0, 1, At, B1); PG8_BAR; PG8_SCHED;
;             PG8_LDA(At, 0, 1); PG8_STAGE(PG8_SB(0, 0), b2, voffB); PG8_STAGE(PG8_SB(0, 1), b2 + hstep, voffB); PG8_STAGE(PG8_SA(0, 0), a2, voffA);
;             PG8_WAIT_V(8); PG8_WAIT_L(0); PG8_BAR; PG8_MMA(1, 0, At, B0); PG8_MMA(1, 1, At, B1); PG8_BAR; PG8_SCHED;
;             PG8_LDB(B0, 1, 0); PG8_LDB(B1, 1, 1); PG8_SCHED; PG8_LDA(At, 1, 0); PG8_STAGE(PG8_SA(0, 1), a2 + hstep, voffA);
;             PG8_WAIT_V(8); PG8_WAIT_L(0); PG8_BAR; PG8_MMA(0, 0, At, B0); PG8_MMA(0, 1, At, B1); PG8_BAR; PG8_SCHED;
;             PG8_LDA(At, 1, 1); PG8_STAGE(PG8_SB(1, 0), b3, voffB); PG8_STAGE(PG8_SB(1, 1), b3 + hstep, voffB); PG8_STAGE(PG8_SA(1, 0), a3, voffA);
;             PG8_WAIT_V(8); PG8_WAIT_L(0); PG8_BAR; PG8_MMA(1, 0, At, B0); PG8_MMA(1, 1, At, B1); PG8_BAR; PG8_SCHED;
	ds_read_b128 v[114:117], v244
	ds_read_b128 v[118:121], v244 offset:1024
	ds_read_b128 v[130:133], v244 offset:2048
	ds_read_b128 v[134:137], v244 offset:3072
	s_add_u32 s50, s42, 0x80000
	s_addc_u32 s51, s43, 0
	s_mov_b32 m0, s10
	ds_read_b128 v[180:183], v178 offset:32768
	ds_read_b128 v[184:187], v178 offset:33792
	ds_read_b128 v[188:191], v178 offset:34816
	ds_read_b128 v[192:195], v178 offset:35840
	ds_read_b128 v[196:199], v178 offset:36864
	ds_read_b128 v[200:203], v178 offset:37888
	ds_read_b128 v[208:211], v178 offset:38912
	ds_read_b128 v[230:233], v178 offset:39936
	global_load_lds_dwordx4 v158, s[50:51]
	s_mov_b32 m0, s11
	s_nop 0
	global_load_lds_dwordx4 v156, s[50:51]
	s_waitcnt vmcnt(6)
	s_waitcnt lgkmcnt(0)
	s_barrier
	v_mfma_f32_16x16x32_bf16 v[142:145], v[114:117], v[180:183], v[142:145]
	v_mfma_f32_16x16x32_bf16 v[138:141], v[130:133], v[180:183], v[138:141]
	v_mfma_f32_16x16x32_bf16 v[110:113], v[114:117], v[188:191], v[110:113]
	v_mfma_f32_16x16x32_bf16 v[106:109], v[130:133], v[188:191], v[106:109]
	v_mfma_f32_16x16x32_bf16 v[94:97], v[114:117], v[196:199], v[94:97]
	v_mfma_f32_16x16x32_bf16 v[90:93], v[130:133], v[196:199], v[90:93]
	v_mfma_f32_16x16x32_bf16 v[78:81], v[114:117], v[208:211], v[78:81]
	v_mfma_f32_16x16x32_bf16 v[74:77], v[130:133], v[208:211], v[74:77]
	v_mfma_f32_16x16x32_bf16 v[142:145], v[118:121], v[184:187], v[142:145]
	v_mfma_f32_16x16x32_bf16 v[138:141], v[134:137], v[184:187], v[138:141]
	v_mfma_f32_16x16x32_bf16 v[110:113], v[118:121], v[192:195], v[110:113]
	v_mfma_f32_16x16x32_bf16 v[106:109], v[134:137], v[192:195], v[106:109]
	v_mfma_f32_16x16x32_bf16 v[94:97], v[118:121], v[200:203], v[94:97]
	v_mfma_f32_16x16x32_bf16 v[90:93], v[134:137], v[200:203], v[90:93]
	v_mfma_f32_16x16x32_bf16 v[78:81], v[118:121], v[230:233], v[78:81]
	v_mfma_f32_16x16x32_bf16 v[74:77], v[134:137], v[230:233], v[74:77]
	s_barrier
	s_add_i32 vcc_lo, s90, s6
	s_add_u32 s50, s40, 0x80
	s_addc_u32 s51, s41, 0
	s_mov_b32 m0, vcc_lo
	ds_read_b128 v[180:183], v178 offset:49152
	ds_read_b128 v[184:187], v178 offset:50176
	ds_read_b128 v[188:191], v178 offset:51200
	ds_read_b128 v[192:195], v178 offset:52224
	ds_read_b128 v[196:199], v178 offset:53248
	ds_read_b128 v[200:203], v178 offset:54272
	ds_read_b128 v[208:211], v178 offset:55296
	ds_read_b128 v[230:233], v178 offset:56320
	global_load_lds_dwordx4 v0, s[50:51]
	s_add_i32 m0, vcc_lo, 0x2000
	s_nop 0
	global_load_lds_dwordx4 v154, s[50:51]
	s_add_u32 s50, s42, 0x80
	s_addc_u32 s51, s43, 0
	s_mov_b32 m0, s13
	s_nop 0
	global_load_lds_dwordx4 v158, s[50:51]
	s_mov_b32 m0, s25
	s_nop 0
	global_load_lds_dwordx4 v156, s[50:51]
	s_waitcnt vmcnt(6)
	s_waitcnt lgkmcnt(0)
	s_barrier
	v_mfma_f32_16x16x32_bf16 v[62:65], v[114:117], v[180:183], v[62:65]
	v_mfma_f32_16x16x32_bf16 v[58:61], v[130:133], v[180:183], v[58:61]
	v_mfma_f32_16x16x32_bf16 v[46:49], v[114:117], v[188:191], v[46:49]
	v_mfma_f32_16x16x32_bf16 v[42:45], v[130:133], v[188:191], v[42:45]
	v_mfma_f32_16x16x32_bf16 v[30:33], v[114:117], v[196:199], v[30:33]
	v_mfma_f32_16x16x32_bf16 v[26:29], v[130:133], v[196:199], v[26:29]
	v_mfma_f32_16x16x32_bf16 v[14:17], v[114:117], v[208:211], v[14:17]
	v_mfma_f32_16x16x32_bf16 v[10:13], v[130:133], v[208:211], v[10:13]
	v_mfma_f32_16x16x32_bf16 v[62:65], v[118:121], v[184:187], v[62:65]
	v_mfma_f32_16x16x32_bf16 v[58:61], v[134:137], v[184:187], v[58:61]
	v_mfma_f32_16x16x32_bf16 v[46:49], v[118:121], v[192:195], v[46:49]
	v_mfma_f32_16x16x32_bf16 v[42:45], v[134:137], v[192:195], v[42:45]
	v_mfma_f32_16x16x32_bf16 v[30:33], v[118:121], v[200:203], v[30:33]
	v_mfma_f32_16x16x32_bf16 v[26:29], v[134:137], v[200:203], v[26:29]
	v_mfma_f32_16x16x32_bf16 v[14:17], v[118:121], v[230:233], v[14:17]
	v_mfma_f32_16x16x32_bf16 v[10:13], v[134:137], v[230:233], v[10:13]
	s_add_i32 s46, s46, 2
	s_add_u32 s34, s34, 0x100
	s_addc_u32 s35, s35, 0
	s_add_u32 s44, s44, 0x100
	s_addc_u32 s45, s45, 0
	s_cmp_gt_u32 s46, 29
	s_barrier
	s_cbranch_scc0 .Ltail_loop
	s_branch .Ltail_join
